# scan loader waves: loop-invariant LDS sub-offset select hoisted out of the chunk loop (-56 instructions per chunk), byte phases of scan body and later code kept by never-executed padding
# speedup vs baseline: 1.0085x; 1.0085x over previous
; #define LAS __attribute__((address_space(3)))
; __device__ __forceinline__ float bflo(unsigned w) { return __uint_as_float(w << 16); }
; __device__ __forceinline__ float bfhi(unsigned w) { return __uint_as_float(w & 0xffff0000u); }
; __device__ __forceinline__ void scan_load_chunk(LAS unsigned char* slot, const float* Wd, const float* V, const bf16_t* RKKB, int p, int rg, int s0, int lt) {
;     ...
;     for (int j = 2; j < 6; ++j) { const int k = lt + 256 * (j - 2), st = k >> 5, rem = k & 31, q = rem >> 3, part = rem & 7; const u32x4 w = r[j];
;         const int Q = (q == 0) ? 4 : (q == 1) ? 2 : (q == 2) ? 3 : 1;
;         LAS f32x4* d = (LAS f32x4*)(slot + st * SCAN_STEP_B + Q * 256 + part * 32);
;         d[0] = (f32x4){bflo(w.x), bfhi(w.x), bflo(w.y), bfhi(w.y)}; d[1] = (f32x4){bflo(w.z), bfhi(w.z), bflo(w.w), bfhi(w.w)}; }
;     if (lt < 128) { const int st = lt >> 2, hf = lt & 3; *(LAS u32x4*)(slot + st * SCAN_STEP_B + 1280 + hf * 16) = r[6]; }
; }
; __device__ __forceinline__ void rwkv_scan_unit(LAS unsigned char* lds, const float* Wd, const float* V, const bf16_t* RKKB, float* Yraw, int p, int rg, int tid) {
;     const int lane = tid & 63, wave = __builtin_amdgcn_readfirstlane(tid >> 6);
;     constexpr int NCH = SEQ / SCAN_CH;
;     scan_load_chunk(lds + (tid >> 8) * SCAN_SLOT_B, Wd, V, RKKB, p, rg, (tid >> 8) * SCAN_CH, tid & 255);
;     __syncthreads();
;     f32x4 S = (f32x4){0.f, 0.f, 0.f, 0.f};
;     const int kq = lane & 15, rl = wave * 4 + (lane >> 4);
;     for (int c = 0; c < NCH; ++c) {
;         if (wave >= 4) { if (c + 2 < NCH) scan_load_chunk(lds + ((c + 2) % 3) * SCAN_SLOT_B, Wd, V, RKKB, p, rg, (c + 2) * SCAN_CH, tid - 256); }
;         else {
;             LAS const unsigned char* sl = lds + (c % 3) * SCAN_SLOT_B + kq * 16;
;             LAS const unsigned char* vl = lds + (c % 3) * SCAN_SLOT_B + 1280 + rl * 4;
;             float* yo = Yraw + ((size_t)p * SEQ + c * SCAN_CH + kq) * 64 + rg * 16 + rl;
;             f32x4 w = *(LAS const f32x4*)(sl), b = *(LAS const f32x4*)(sl + 256), k = *(LAS const f32x4*)(sl + 512), kk = *(LAS const f32x4*)(sl + 768), r = *(LAS const f32x4*)(sl + 1024);
.LBB0_340:
	s_or_b64 exec, exec, s[6:7]
	v_add3_u32 v14, v14, v10, v22
	s_waitcnt vmcnt(0)
	v_lshlrev_b32_e32 v10, 16, v2
	v_and_b32_e32 v11, 0xffff0000, v2
	v_lshlrev_b32_e32 v12, 16, v3
	v_and_b32_e32 v13, 0xffff0000, v3
	v_lshlrev_b32_e32 v2, 16, v4
	v_and_b32_e32 v3, 0xffff0000, v4
	v_lshlrev_b32_e32 v4, 16, v5
	v_and_b32_e32 v5, 0xffff0000, v5
	ds_write_b128 v14, v[10:13] offset:10752
	ds_write_b128 v14, v[2:5] offset:10768
	s_and_saveexec_b64 s[6:7], s[4:5]
	v_lshrrev_b32_e32 v2, 8, v232
	v_lshlrev_b32_e32 v2, 11, v2
	v_and_b32_e32 v3, 3, v232
	v_lshl_or_b32 v2, v3, 9, v2
	v_and_b32_e32 v3, 0xfc, v232
	v_or_b32_e32 v2, v2, v3
	v_add_u32_e32 v2, 0x1f800, v2
	ds_write_b32 v2, v6
	ds_write_b32 v2, v7 offset:128
	ds_write_b32 v2, v8 offset:256
	ds_write_b32 v2, v9 offset:384
	s_or_b64 exec, exec, s[6:7]
	v_and_b32_e32 v3, 4, v32
	v_cmp_eq_u32_e64 s[6:7], 0, v3
	v_and_b32_e32 v3, 1, v32
	s_ashr_i32 s4, s10, 6
	v_and_b32_e32 v4, 2, v32
	v_cmp_eq_u32_e64 s[10:11], 0, v3
	v_add_u32_e32 v3, 0xffffff00, v32
	v_add_u32_e32 v12, 0x100, v32
	v_add_u32_e32 v14, 0x200, v32
	s_cmp_lt_i32 s4, 4
	v_cmp_eq_u32_e64 s[8:9], 0, v4
	v_ashrrev_i32_e32 v4, 4, v3
	v_ashrrev_i32_e32 v6, 4, v32
	v_ashrrev_i32_e32 v8, 5, v3
	v_ashrrev_i32_e32 v10, 5, v32
	v_ashrrev_i32_e32 v12, 5, v12
	v_ashrrev_i32_e32 v14, 5, v14
	v_ashrrev_i32_e32 v16, 2, v3
	s_movk_i32 s19, 0x540
	s_cselect_b64 s[16:17], -1, 0
	v_mul_lo_u32 v74, v4, s19
	v_mul_lo_u32 v75, v6, s19
	v_mul_lo_u32 v77, v8, s19
	v_mul_lo_u32 v78, v10, s19
	v_mul_lo_u32 v79, v12, s19
	v_mul_lo_u32 v80, v14, s19
	v_mul_lo_u32 v81, v16, s19
	s_and_b32 s23, s20, 7
	s_ashr_i32 s19, s18, 31
	s_lshl_b32 s21, s23, 22
	s_lshl_b64 s[24:25], s[18:19], 20
	v_ashrrev_i32_e32 v17, 31, v16
	v_lshlrev_b32_e32 v19, 5, v32
	s_add_u32 s24, s21, s24
	v_and_b32_e32 v76, 0xe0, v19
	s_addc_u32 s25, 0, s25
	v_lshlrev_b64 v[16:17], 8, v[16:17]
	s_lshl_b32 s20, s20, 3
	v_and_b32_e32 v19, 3, v3
	v_lshl_add_u64 v[16:17], s[24:25], 0, v[16:17]
	s_and_b32 s26, s20, 0xc0
	v_lshlrev_b32_e32 v19, 4, v19
	v_readlane_b32 s20, v254, 47
	v_or3_b32 v16, v16, s26, v19
	v_readlane_b32 s21, v254, 48
	s_lshl_b32 s27, s23, 23
	v_ashrrev_i32_e32 v5, 31, v4
	v_lshl_add_u64 v[46:47], s[20:21], 0, v[16:17]
	s_lshl_b64 s[20:21], s[18:19], 21
	v_ashrrev_i32_e32 v7, 31, v6
	v_ashrrev_i32_e32 v9, 31, v8
	v_ashrrev_i32_e32 v11, 31, v10
	v_ashrrev_i32_e32 v13, 31, v12
	v_ashrrev_i32_e32 v15, 31, v14
	s_add_u32 s20, s27, s20
	v_lshlrev_b32_e32 v18, 4, v3
	s_addc_u32 s21, 0, s21
	v_lshlrev_b64 v[14:15], 9, v[14:15]
	v_lshlrev_b64 v[12:13], 9, v[12:13]
	v_lshlrev_b64 v[10:11], 9, v[10:11]
	v_lshlrev_b64 v[8:9], 9, v[8:9]
	v_lshlrev_b64 v[6:7], 8, v[6:7]
	v_lshlrev_b64 v[4:5], 8, v[4:5]
	v_and_b32_e32 v73, 0xf0, v18
	v_lshl_add_u64 v[14:15], s[20:21], 0, v[14:15]
	v_lshl_add_u64 v[12:13], s[20:21], 0, v[12:13]
	v_lshl_add_u64 v[10:11], s[20:21], 0, v[10:11]
	v_lshl_add_u64 v[8:9], s[20:21], 0, v[8:9]
	v_lshl_add_u64 v[6:7], s[24:25], 0, v[6:7]
	v_readlane_b32 s20, v254, 51
	v_lshl_add_u64 v[4:5], s[24:25], 0, v[4:5]
	v_or_b32_e32 v6, v6, v73
	v_readlane_b32 s21, v254, 52
	v_or_b32_e32 v4, v4, v73
	s_lshl_b64 s[18:19], s[18:19], 12
	v_lshl_add_u64 v[56:57], s[20:21], 0, v[6:7]
	v_lshl_add_u64 v[58:59], s[20:21], 0, v[4:5]
	s_lshl_b32 s20, s23, 14
	s_add_u32 s18, s20, s18
	v_and_b32_e32 v0, 15, v32
	s_addc_u32 s19, 0, s19
	v_bfe_u32 v2, v32, 4, 2
	v_and_b32_e32 v3, 7, v3
	v_or_b32_e32 v4, s18, v0
	v_mov_b32_e32 v5, s19
	v_lshl_or_b32 v2, s4, 2, v2
	v_and_b32_e32 v16, 0x180, v18
	v_lshlrev_b32_e32 v3, 4, v3
	v_lshlrev_b64 v[4:5], 8, v[4:5]
	v_or3_b32 v14, v14, v16, v3
	v_or3_b32 v12, v12, v16, v3
	v_or3_b32 v10, v10, v16, v3
	v_or3_b32 v8, v8, v16, v3
	v_or_b32_e32 v4, s26, v4
	v_ashrrev_i32_e32 v3, 31, v2
	v_lshlrev_b32_e32 v72, 2, v2
	v_lshl_add_u64 v[2:3], v[2:3], 2, v[4:5]
	v_readlane_b32 s28, v254, 49
	v_lshl_add_u64 v[60:61], s[92:93], 0, v[2:3]
	v_mov_b32_e32 v2, v1
	v_mov_b32_e32 v3, v1
	v_lshlrev_b32_e32 v71, 4, v0
	v_cmp_gt_u32_e64 s[4:5], 8, v0
	s_movk_i32 s12, 0x180
	v_readlane_b32 s29, v254, 50
	v_mov_b32_e32 v0, v1
	v_mov_b64_e32 v[4:5], v[2:3]
	s_mov_b32 s22, 0
	v_cmp_gt_i32_e64 s[12:13], s12, v32
	v_and_b32_e32 v82, 48, v18
	v_lshl_add_u64 v[48:49], s[28:29], 0, v[14:15]
	v_lshl_add_u64 v[50:51], s[28:29], 0, v[12:13]
	v_lshl_add_u64 v[52:53], s[28:29], 0, v[10:11]
	v_lshl_add_u64 v[54:55], s[28:29], 0, v[8:9]
	v_mov_b64_e32 v[2:3], v[0:1]
	s_waitcnt lgkmcnt(0)
	s_barrier
	s_and_b64 vcc, exec, s[16:17]
	s_cbranch_vccz .Lscan_ldprime
	s_setprio 3
	v_lshlrev_b32_e32 v96, 5, v72
	v_add_u32_e32 v96, 0x1f800, v96
	ds_read_b128 v[116:119], v96
	ds_read_b128 v[132:135], v71 offset:768
	ds_read_b128 v[120:123], v71
	ds_read_b128 v[128:131], v71 offset:512
	ds_read_b128 v[124:127], v71 offset:256
	ds_read_b128 v[136:139], v71 offset:1024
	ds_read_b128 v[156:159], v71 offset:2112
	ds_read_b128 v[144:147], v71 offset:1344
	ds_read_b128 v[152:155], v71 offset:1856
	ds_read_b128 v[148:151], v71 offset:1600
	ds_read_b128 v[160:163], v71 offset:2368
	s_branch .Lscan_noprime
	s_nop 0
	s_nop 0
	s_nop 0
	s_nop 0
	s_nop 0
	s_nop 0
	s_nop 0
.Lscan_ldprime:
	v_mov_b32_e32 v136, 0x400
	v_cmp_lt_i32_e32 vcc, 0, v69
	v_mov_b32_e32 v137, 0x200
	v_cndmask_b32_e32 v136, v136, v70, vcc
	v_cmp_eq_u32_e32 vcc, 1, v69
	s_nop 0
	v_cndmask_b32_e32 v136, v136, v137, vcc
	v_lshl_add_u64 v[134:135], v[58:59], 0, s[14:15]
	global_load_dwordx4 v[130:133], v[134:135], off
	v_lshl_add_u64 v[134:135], v[56:57], 0, s[14:15]
	global_load_dwordx4 v[126:129], v[134:135], off
	v_lshl_add_u64 v[134:135], v[54:55], 0, s[14:15]
	global_load_dwordx4 v[122:125], v[134:135], off
	v_lshl_add_u64 v[134:135], v[52:53], 0, s[14:15]
	global_load_dwordx4 v[118:121], v[134:135], off
	v_lshl_add_u64 v[134:135], v[50:51], 0, s[14:15]
	global_load_dwordx4 v[114:117], v[134:135], off
	v_lshl_add_u64 v[134:135], v[48:49], 0, s[14:15]
	global_load_dwordx4 v[106:109], v[134:135], off
	v_mov_b32_e32 v110, 0
	v_mov_b32_e32 v111, 0
	v_mov_b32_e32 v112, 0
	v_mov_b32_e32 v113, 0
	s_and_saveexec_b64 s[18:19], s[12:13]
	v_lshl_add_u64 v[134:135], v[46:47], 0, s[14:15]
	global_load_dwordx4 v[110:113], v[134:135], off
	s_or_b64 exec, exec, s[18:19]

; #define LAS __attribute__((address_space(3)))
; __device__ __forceinline__ float bflo(unsigned w) { return __uint_as_float(w << 16); }
; __device__ __forceinline__ float bfhi(unsigned w) { return __uint_as_float(w & 0xffff0000u); }
; __device__ __forceinline__ void scan_load_chunk(LAS unsigned char* slot, const float* Wd, const float* V, const bf16_t* RKKB, int p, int rg, int s0, int lt) {
;     ...
;     for (int j = 0; j < 2; ++j) { const int idx = lt + 256 * j, st = idx >> 4, part = idx & 15; *(LAS u32x4*)(slot + st * SCAN_STEP_B + part * 16) = r[j]; }
; #pragma unroll
;     for (int j = 2; j < 6; ++j) { const int k = lt + 256 * (j - 2), st = k >> 5, rem = k & 31, q = rem >> 3, part = rem & 7; const u32x4 w = r[j];
;         const int Q = (q == 0) ? 4 : (q == 1) ? 2 : (q == 2) ? 3 : 1;
;         LAS f32x4* d = (LAS f32x4*)(slot + st * SCAN_STEP_B + Q * 256 + part * 32);
;         d[0] = (f32x4){bflo(w.x), bfhi(w.x), bflo(w.y), bfhi(w.y)}; d[1] = (f32x4){bflo(w.z), bfhi(w.z), bflo(w.w), bfhi(w.w)}; }
;     if (lt < 128) { const int st = lt >> 2, hf = lt & 3; *(LAS u32x4*)(slot + st * SCAN_STEP_B + 1280 + hf * 16) = r[6]; }
.LBB0_348:
	s_andn2_b64 vcc, exec, s[18:19]
	s_cbranch_vccnz .LBB0_345
	s_cmpk_gt_u32 s22, 0x7d
	s_cbranch_scc1 .LBB0_344
	s_add_i32 s18, s22, 2
	s_mul_i32 s19, s18, 0xab
	s_bfe_u32 s19, s19, 0x70009
	s_mul_i32 s19, s19, 3
	s_sub_i32 s18, s18, s19
	s_and_b32 s18, s18, 0xff
	s_mul_i32 s18, s18, 0xa800
	s_add_i32 s23, s18, 0
	v_add_u32_e32 v0, s23, v73
	v_add_u32_e32 v34, v0, v74
	v_add_u32_e32 v0, v0, v75
	s_waitcnt vmcnt(0)
	ds_write_b128 v34, v[130:133]
	ds_write_b128 v0, v[126:129]
	v_add_u32_e32 v26, s23, v77
	v_add3_u32 v0, v26, v136, v76
	v_lshlrev_b32_e32 v26, 16, v122
	v_and_b32_e32 v27, 0xffff0000, v122
	v_lshlrev_b32_e32 v28, 16, v123
	v_and_b32_e32 v29, 0xffff0000, v123
	v_lshlrev_b32_e32 v22, 16, v124
	v_and_b32_e32 v23, 0xffff0000, v124
	v_lshlrev_b32_e32 v24, 16, v125
	v_and_b32_e32 v25, 0xffff0000, v125
	ds_write_b128 v0, v[26:29]
	ds_write_b128 v0, v[22:25] offset:16
	v_add_u32_e32 v22, s23, v78
	v_add3_u32 v0, v22, v136, v76
	v_lshlrev_b32_e32 v22, 16, v118
	v_and_b32_e32 v23, 0xffff0000, v118
	v_lshlrev_b32_e32 v24, 16, v119
	v_and_b32_e32 v25, 0xffff0000, v119
	v_lshlrev_b32_e32 v18, 16, v120
	v_and_b32_e32 v19, 0xffff0000, v120
	v_lshlrev_b32_e32 v20, 16, v121
	v_and_b32_e32 v21, 0xffff0000, v121
	ds_write_b128 v0, v[22:25]
	ds_write_b128 v0, v[18:21] offset:16
	v_add_u32_e32 v18, s23, v79
	v_add3_u32 v0, v18, v136, v76
	v_lshlrev_b32_e32 v18, 16, v114
	v_and_b32_e32 v19, 0xffff0000, v114
	v_lshlrev_b32_e32 v20, 16, v115
	v_and_b32_e32 v21, 0xffff0000, v115
	v_lshlrev_b32_e32 v14, 16, v116
	v_and_b32_e32 v15, 0xffff0000, v116
	v_lshlrev_b32_e32 v16, 16, v117
	v_and_b32_e32 v17, 0xffff0000, v117
	ds_write_b128 v0, v[18:21]
	ds_write_b128 v0, v[14:17] offset:16
	v_add_u32_e32 v14, s23, v80
	v_add3_u32 v0, v14, v136, v76
	v_lshlrev_b32_e32 v14, 16, v106
	v_and_b32_e32 v15, 0xffff0000, v106
	v_lshlrev_b32_e32 v16, 16, v107
	v_and_b32_e32 v17, 0xffff0000, v107
	v_lshlrev_b32_e32 v6, 16, v108
	v_and_b32_e32 v7, 0xffff0000, v108
	v_lshlrev_b32_e32 v8, 16, v109
	v_and_b32_e32 v9, 0xffff0000, v109
	ds_write_b128 v0, v[14:17]
	ds_write_b128 v0, v[6:9] offset:16
	s_and_saveexec_b64 s[18:19], s[12:13]
	s_cbranch_execz .LBB0_343
	s_lshr_b32 s20, s23, 15
	s_lshl_b32 s20, s20, 11
	s_add_i32 s20, s20, 0x1f800
	v_and_b32_e32 v14, 0xfc, v232
	v_and_b32_e32 v0, 3, v232
	v_lshl_or_b32 v0, v0, 9, v14
	v_add_u32_e32 v0, s20, v0
	ds_write_b32 v0, v110
	ds_write_b32 v0, v111 offset:128
	ds_write_b32 v0, v112 offset:256
	ds_write_b32 v0, v113 offset:384
	s_branch .LBB0_343
	s_nop 0
	s_nop 0
	s_nop 0
	s_nop 0
	s_nop 0
	s_nop 0
	s_nop 0
	s_nop 0
	s_nop 0
	s_nop 0
	s_nop 0
	s_nop 0
